# hyena filter MLP (prep phase): weights preloaded once per wave into VGPRs, lane broadcast via v_readlane instead of per-token global loads + bpermute; plus removed epilogue store drains and duplicate
# speedup vs baseline: 1.0163x; 1.0163x over previous
; __device__ __forceinline__ unsigned cvt_pk_bf16(float lo, float hi) { unsigned r; asm volatile("v_cvt_pk_bf16_f32 %0, %1, %2" : "=v"(r) : "v"(lo), "v"(hi)); return r; }
;   __device__ __forceinline__ void operator()(const f32x4 (&acc)[2][2][4][2], const Unit& u, int wr, int wc, int fr, int fq) const {
;     ...
;       for (int bj = 0; bj < 2; ++bj) {
;         f32x4 b0 = (f32x4){0.f, 0.f, 0.f, 0.f}, b1 = b0;
;         if (bias) { b0 = *(const f32x4*)(bias + bcol0 + bj * HALF); b1 = *(const f32x4*)(bias + bcol0 + bj * HALF + 4); }
; #pragma unroll
;         for (int ai = 0; ai < 2; ++ai)
; #pragma unroll
;           for (int m = 0; m < 4; ++m) {
;             bf16_t* rowp = base + (size_t)(row0 + ai * HALF + m * 16) * ldc + col0 + bj * HALF;
;             const f32x4 v0 = acc[ai][bj][m][0] + b0, v1 = acc[ai][bj][m][1] + b1;
;             u32x4 o; o.x = cvt_pk_bf16(v0[0], v0[1]); o.y = cvt_pk_bf16(v0[2], v0[3]); o.z = cvt_pk_bf16(v1[0], v1[1]); o.w = cvt_pk_bf16(v1[2], v1[3]);
;             *(u32x4*)rowp = o;
;           }
.LBB0_285:
	v_pk_add_f32 v[62:63], v[62:63], v[66:67]
	v_pk_add_f32 v[60:61], v[60:61], v[64:65]
	v_pk_add_f32 v[68:69], v[58:59], v[130:131]
	v_pk_add_f32 v[58:59], v[56:57], v[128:129]
	v_cvt_pk_bf16_f32 v56, v60, v61
	v_cvt_pk_bf16_f32 v57, v62, v63
	v_pk_add_f32 v[54:55], v[54:55], v[66:67]
	v_cvt_pk_bf16_f32 v58, v58, v59
	v_cvt_pk_bf16_f32 v59, v68, v69
	global_store_dwordx4 v[160:161], v[56:59], off offset:256
	v_pk_add_f32 v[52:53], v[52:53], v[64:65]
	v_pk_add_f32 v[46:47], v[46:47], v[66:67]
	v_pk_add_f32 v[56:57], v[50:51], v[130:131]
	v_pk_add_f32 v[50:51], v[48:49], v[128:129]
	v_cvt_pk_bf16_f32 v48, v52, v53
	v_cvt_pk_bf16_f32 v49, v54, v55
	v_pk_add_f32 v[44:45], v[44:45], v[64:65]
	v_cvt_pk_bf16_f32 v50, v50, v51
	v_cvt_pk_bf16_f32 v51, v56, v57
	global_store_dwordx4 v[120:121], v[48:51], off offset:256
	v_pk_add_f32 v[38:39], v[38:39], v[66:67]
	v_pk_add_f32 v[36:37], v[36:37], v[64:65]
	v_pk_add_f32 v[48:49], v[42:43], v[130:131]
	v_pk_add_f32 v[42:43], v[40:41], v[128:129]
	v_cvt_pk_bf16_f32 v40, v44, v45
	v_cvt_pk_bf16_f32 v41, v46, v47
	v_pk_add_f32 v[30:31], v[30:31], v[66:67]
	v_cvt_pk_bf16_f32 v42, v42, v43
	v_cvt_pk_bf16_f32 v43, v48, v49
	global_store_dwordx4 v[112:113], v[40:43], off offset:256
	v_pk_add_f32 v[28:29], v[28:29], v[64:65]
	v_pk_add_f32 v[22:23], v[22:23], v[66:67]
	v_pk_add_f32 v[40:41], v[34:35], v[130:131]
	v_pk_add_f32 v[34:35], v[32:33], v[128:129]
	v_cvt_pk_bf16_f32 v32, v36, v37
	v_cvt_pk_bf16_f32 v33, v38, v39
	v_pk_add_f32 v[20:21], v[20:21], v[64:65]
	v_cvt_pk_bf16_f32 v34, v34, v35
	v_cvt_pk_bf16_f32 v35, v40, v41
	global_store_dwordx4 v[104:105], v[32:35], off offset:256
	v_pk_add_f32 v[14:15], v[14:15], v[66:67]
	v_pk_add_f32 v[12:13], v[12:13], v[64:65]
	v_pk_add_f32 v[32:33], v[26:27], v[130:131]
	v_pk_add_f32 v[26:27], v[24:25], v[128:129]
	v_cvt_pk_bf16_f32 v24, v28, v29
	v_cvt_pk_bf16_f32 v25, v30, v31
	v_pk_add_f32 v[6:7], v[6:7], v[66:67]
	v_cvt_pk_bf16_f32 v26, v26, v27
	v_cvt_pk_bf16_f32 v27, v32, v33
	global_store_dwordx4 v[96:97], v[24:27], off offset:256
	v_pk_add_f32 v[4:5], v[4:5], v[64:65]
	s_nop 0
	v_pk_add_f32 v[24:25], v[18:19], v[130:131]
	v_pk_add_f32 v[18:19], v[16:17], v[128:129]
	v_cvt_pk_bf16_f32 v16, v20, v21
	v_cvt_pk_bf16_f32 v17, v22, v23
	s_nop 0
	v_cvt_pk_bf16_f32 v18, v18, v19
	v_cvt_pk_bf16_f32 v19, v24, v25
	global_store_dwordx4 v[88:89], v[16:19], off offset:256
	s_nop 1
	v_pk_add_f32 v[16:17], v[10:11], v[130:131]
	v_pk_add_f32 v[10:11], v[8:9], v[128:129]
	v_cvt_pk_bf16_f32 v8, v12, v13
	v_cvt_pk_bf16_f32 v9, v14, v15
	s_nop 0
	v_cvt_pk_bf16_f32 v10, v10, v11
	v_cvt_pk_bf16_f32 v11, v16, v17
	global_store_dwordx4 v[80:81], v[8:11], off offset:256
	s_nop 1
	v_pk_add_f32 v[8:9], v[2:3], v[130:131]
	v_pk_add_f32 v[2:3], v[0:1], v[128:129]
	v_cvt_pk_bf16_f32 v0, v4, v5
	v_cvt_pk_bf16_f32 v1, v6, v7
	s_nop 0
	v_cvt_pk_bf16_f32 v2, v2, v3
	v_cvt_pk_bf16_f32 v3, v8, v9
	global_store_dwordx4 v[72:73], v[0:3], off offset:256

; __device__ __forceinline__ void gemm_phase(LAS unsigned char* lds, const Gemm g, const StaticOrder& S, const Epi& E, const int tid) {
;     ...
;     for (int a = 0; a < 2; ++a)
; #pragma unroll
;       for (int b = 0; b < 2; ++b)
; #pragma unroll
;         for (int m = 0; m < 4; ++m)
; #pragma unroll
;           for (int n = 0; n < 2; ++n) acc[a][b][m][n] = (f32x4){0.f, 0.f, 0.f, 0.f};
;     cur = nxt; cA = nA; cB = nB; ++ui;
.LBB0_297:
	v_mov_b32_e32 v127, 0
	s_andn2_b64 vcc, exec, s[46:47]
	v_mov_b32_e32 v126, v127
	v_mov_b32_e32 v125, v127
	v_mov_b32_e32 v124, v127
	v_mov_b32_e32 v123, v127
	v_mov_b32_e32 v122, v127
	v_mov_b32_e32 v121, v127
	v_mov_b32_e32 v120, v127
	v_mov_b32_e32 v119, v127
	v_mov_b32_e32 v118, v127
	v_mov_b32_e32 v117, v127
	v_mov_b32_e32 v116, v127
	v_mov_b32_e32 v115, v127
	v_mov_b32_e32 v114, v127
	v_mov_b32_e32 v113, v127
	v_mov_b32_e32 v112, v127
	v_mov_b32_e32 v111, v127
	v_mov_b32_e32 v110, v127
	v_mov_b32_e32 v109, v127
	v_mov_b32_e32 v108, v127
	v_mov_b32_e32 v107, v127
	v_mov_b32_e32 v106, v127
	v_mov_b32_e32 v105, v127
	v_mov_b32_e32 v104, v127
	v_mov_b32_e32 v103, v127
	v_mov_b32_e32 v102, v127
	v_mov_b32_e32 v101, v127
	v_mov_b32_e32 v100, v127
	v_mov_b32_e32 v99, v127
	v_mov_b32_e32 v98, v127
	v_mov_b32_e32 v97, v127
	v_mov_b32_e32 v96, v127
	v_mov_b32_e32 v63, v127
	v_mov_b32_e32 v62, v127
	v_mov_b32_e32 v61, v127
	v_mov_b32_e32 v60, v127
	v_mov_b32_e32 v59, v127
	v_mov_b32_e32 v58, v127
	v_mov_b32_e32 v57, v127
	v_mov_b32_e32 v56, v127
	v_mov_b32_e32 v55, v127
	v_mov_b32_e32 v54, v127
	v_mov_b32_e32 v53, v127
	v_mov_b32_e32 v52, v127
	v_mov_b32_e32 v51, v127
	v_mov_b32_e32 v50, v127
	v_mov_b32_e32 v49, v127
	v_mov_b32_e32 v48, v127
	v_mov_b32_e32 v47, v127
	v_mov_b32_e32 v46, v127
	v_mov_b32_e32 v45, v127
	v_mov_b32_e32 v44, v127
	v_mov_b32_e32 v43, v127
	v_mov_b32_e32 v42, v127
	v_mov_b32_e32 v41, v127
	v_mov_b32_e32 v40, v127
	v_mov_b32_e32 v39, v127
	v_mov_b32_e32 v38, v127
	v_mov_b32_e32 v37, v127
	v_mov_b32_e32 v36, v127
	v_mov_b32_e32 v35, v127
	v_mov_b32_e32 v34, v127
	v_mov_b32_e32 v33, v127
	v_mov_b32_e32 v32, v127
	v_mov_b32_e32 v95, v127
	v_mov_b32_e32 v94, v127
	v_mov_b32_e32 v93, v127
	v_mov_b32_e32 v92, v127
	v_mov_b32_e32 v91, v127
	v_mov_b32_e32 v90, v127
	v_mov_b32_e32 v89, v127
	v_mov_b32_e32 v88, v127
	v_mov_b32_e32 v87, v127
	v_mov_b32_e32 v86, v127
	v_mov_b32_e32 v85, v127
	v_mov_b32_e32 v84, v127
	v_mov_b32_e32 v83, v127
	v_mov_b32_e32 v82, v127
	v_mov_b32_e32 v81, v127
	v_mov_b32_e32 v80, v127
	v_mov_b32_e32 v79, v127
	v_mov_b32_e32 v78, v127
	v_mov_b32_e32 v77, v127
	v_mov_b32_e32 v76, v127
	v_mov_b32_e32 v75, v127
	v_mov_b32_e32 v74, v127
	v_mov_b32_e32 v73, v127
	v_mov_b32_e32 v72, v127
	v_mov_b32_e32 v71, v127
	v_mov_b32_e32 v70, v127
	v_mov_b32_e32 v69, v127
	v_mov_b32_e32 v68, v127
	v_mov_b32_e32 v67, v127
	v_mov_b32_e32 v66, v127
	v_mov_b32_e32 v65, v127
	v_mov_b32_e32 v64, v127
	v_mov_b32_e32 v31, v127
	v_mov_b32_e32 v30, v127
	v_mov_b32_e32 v29, v127
	v_mov_b32_e32 v28, v127
	v_mov_b32_e32 v27, v127
	v_mov_b32_e32 v26, v127
	v_mov_b32_e32 v25, v127
	v_mov_b32_e32 v24, v127
	v_mov_b32_e32 v23, v127
	v_mov_b32_e32 v22, v127
	v_mov_b32_e32 v21, v127
	v_mov_b32_e32 v20, v127
	v_mov_b32_e32 v19, v127
	v_mov_b32_e32 v18, v127
	v_mov_b32_e32 v17, v127
	v_mov_b32_e32 v16, v127
	v_mov_b32_e32 v15, v127
	v_mov_b32_e32 v14, v127
	v_mov_b32_e32 v13, v127
	v_mov_b32_e32 v12, v127
	v_mov_b32_e32 v11, v127
	v_mov_b32_e32 v10, v127
	v_mov_b32_e32 v9, v127
	v_mov_b32_e32 v8, v127
	v_mov_b32_e32 v7, v127
	v_mov_b32_e32 v6, v127
	v_mov_b32_e32 v5, v127
	v_mov_b32_e32 v4, v127
	v_mov_b32_e32 v3, v127
	v_mov_b32_e32 v2, v127
	v_mov_b32_e32 v1, v127
	v_mov_b32_e32 v0, v127
	s_cbranch_vccnz .LBB0_300
	s_add_u32 vcc_lo, s68, 0x100
	s_addc_u32 vcc_hi, s69, 0
	s_add_u32 s8, s70, 0x80
	s_addc_u32 s9, s71, 0
	s_mov_b32 s10, 0
	s_mov_b64 s[2:3], 0x80

; __device__ __forceinline__ unsigned cvt_pk_bf16(float lo, float hi) { unsigned r; asm volatile("v_cvt_pk_bf16_f32 %0, %1, %2" : "=v"(r) : "v"(lo), "v"(hi)); return r; }
;   __device__ __forceinline__ void operator()(const f32x4 (&acc)[2][2][4][2], const Unit& u, int wr, int wc, int fr, int fq) const {
;     ...
;       const int row0 = u.pm * BM + wr * 64 + fr; int colt = u.pn * BM; bf16_t* base = O;
;       if (split_cols) { const int t = colt / split_cols; base += (size_t)t * split_stride; colt -= t * split_cols; }
;       const int col0 = colt + wc * 32 + 8 * fq, bcol0 = u.pn * BM + wc * 32 + 8 * fq;
; #pragma unroll
;       for (int bj = 0; bj < 2; ++bj) {
;         f32x4 b0 = (f32x4){0.f, 0.f, 0.f, 0.f}, b1 = b0;
;         if (bias) { b0 = *(const f32x4*)(bias + bcol0 + bj * HALF); b1 = *(const f32x4*)(bias + bcol0 + bj * HALF + 4); }
; #pragma unroll
;         for (int ai = 0; ai < 2; ++ai)
; #pragma unroll
;           for (int m = 0; m < 4; ++m) {
;             bf16_t* rowp = base + (size_t)(row0 + ai * HALF + m * 16) * ldc + col0 + bj * HALF;
;             const f32x4 v0 = acc[ai][bj][m][0] + b0, v1 = acc[ai][bj][m][1] + b1;
;             u32x4 o; o.x = cvt_pk_bf16(v0[0], v0[1]); o.y = cvt_pk_bf16(v0[2], v0[3]); o.z = cvt_pk_bf16(v1[0], v1[1]); o.w = cvt_pk_bf16(v1[2], v1[3]);
;             *(u32x4*)rowp = o;
;           }
.LBB0_329:
	v_or_b32_e32 v130, s5, v206
	v_ashrrev_i32_e32 v131, 31, v130
	v_cndmask_b32_e64 v129, 0, 1, s[48:49]
	v_mov_b32_e32 v128, 0
	v_cmp_ne_u32_e64 s[8:9], 1, v129
	s_andn2_b64 vcc, exec, s[48:49]
	v_lshl_add_u64 v[162:163], v[130:131], 2, s[12:13]
	v_mov_b32_e32 v130, 0
	v_mov_b32_e32 v131, 0
	v_mov_b32_e32 v132, 0
	v_mov_b32_e32 v133, 0
	v_mov_b32_e32 v134, 0
	v_mov_b32_e32 v135, 0
	v_mov_b32_e32 v136, 0
	v_mov_b32_e32 v137, 0
	s_cbranch_vccnz .LBB0_331
	global_load_dwordx4 v[130:133], v[162:163], off offset:16
	global_load_dwordx4 v[134:137], v[162:163], off
	s_waitcnt vmcnt(0)
.LBB0_331:
	v_add_u32_e32 v160, s33, v206
	v_ashrrev_i32_e32 v161, 31, v160
	v_ashrrev_i32_e32 v141, 31, v158
	v_lshl_add_u64 v[164:165], v[160:161], 1, s[10:11]
	v_mul_lo_u32 v159, s31, v158
	v_mul_lo_u32 v141, s30, v141
	v_mad_u64_u32 v[160:161], s[10:11], s30, v158, 0
	v_add3_u32 v161, v161, v141, v159
	v_lshl_add_u64 v[160:161], v[160:161], 1, v[164:165]
	v_pk_add_f32 v[124:125], v[124:125], v[134:135]
	v_pk_add_f32 v[166:167], v[122:123], v[132:133]
	v_pk_add_f32 v[122:123], v[120:121], v[130:131]
	v_cvt_pk_bf16_f32 v120, v124, v125
	v_pk_add_f32 v[126:127], v[126:127], v[136:137]
	v_pk_add_f32 v[116:117], v[116:117], v[134:135]
	v_cvt_pk_bf16_f32 v121, v126, v127
	v_cvt_pk_bf16_f32 v122, v122, v123
	v_cvt_pk_bf16_f32 v123, v166, v167
	global_store_dwordx4 v[160:161], v[120:123], off
	v_pk_add_f32 v[118:119], v[118:119], v[136:137]
	v_pk_add_f32 v[108:109], v[108:109], v[134:135]
	v_or_b32_e32 v120, 16, v158
	v_mul_lo_u32 v122, s31, v120
	v_mad_u64_u32 v[120:121], s[10:11], s30, v120, 0
	v_add3_u32 v121, v121, v141, v122
	v_lshl_add_u64 v[120:121], v[120:121], 1, v[164:165]
	v_pk_add_f32 v[122:123], v[114:115], v[132:133]
	v_pk_add_f32 v[114:115], v[112:113], v[130:131]
	v_cvt_pk_bf16_f32 v112, v116, v117
	v_cvt_pk_bf16_f32 v113, v118, v119
	v_pk_add_f32 v[110:111], v[110:111], v[136:137]
	v_cvt_pk_bf16_f32 v114, v114, v115
	v_cvt_pk_bf16_f32 v115, v122, v123
	global_store_dwordx4 v[120:121], v[112:115], off
	v_add_u32_e32 v129, 0x80, v158
	v_ashrrev_i32_e32 v140, 31, v129
	v_or_b32_e32 v112, 32, v158
	v_mul_lo_u32 v114, s31, v112
	v_mad_u64_u32 v[112:113], s[10:11], s30, v112, 0
	v_add3_u32 v113, v113, v141, v114
	v_lshl_add_u64 v[112:113], v[112:113], 1, v[164:165]
	v_pk_add_f32 v[114:115], v[106:107], v[132:133]
	v_pk_add_f32 v[106:107], v[104:105], v[130:131]
	v_cvt_pk_bf16_f32 v104, v108, v109
	v_cvt_pk_bf16_f32 v105, v110, v111
	v_pk_add_f32 v[102:103], v[102:103], v[136:137]
	v_cvt_pk_bf16_f32 v106, v106, v107
	v_cvt_pk_bf16_f32 v107, v114, v115
	global_store_dwordx4 v[112:113], v[104:107], off
	v_pk_add_f32 v[100:101], v[100:101], v[134:135]
	v_pk_add_f32 v[92:93], v[92:93], v[134:135]
	v_or_b32_e32 v104, 48, v158
	v_mul_lo_u32 v106, s31, v104
	v_mad_u64_u32 v[104:105], s[10:11], s30, v104, 0
	v_add3_u32 v105, v105, v141, v106
	v_pk_add_f32 v[106:107], v[98:99], v[132:133]
	v_pk_add_f32 v[98:99], v[96:97], v[130:131]
	v_lshl_add_u64 v[104:105], v[104:105], 1, v[164:165]
	v_cvt_pk_bf16_f32 v96, v100, v101
	v_cvt_pk_bf16_f32 v97, v102, v103
	v_cvt_pk_bf16_f32 v98, v98, v99
	v_cvt_pk_bf16_f32 v99, v106, v107
	global_store_dwordx4 v[104:105], v[96:99], off
	v_pk_add_f32 v[94:95], v[94:95], v[136:137]
	v_pk_add_f32 v[84:85], v[84:85], v[134:135]
	v_mul_lo_u32 v98, s30, v140
	v_mul_lo_u32 v99, s31, v129
	v_mad_u64_u32 v[96:97], s[10:11], s30, v129, 0
	v_add3_u32 v97, v97, v98, v99
	v_lshl_add_u64 v[96:97], v[96:97], 1, v[164:165]
	v_pk_add_f32 v[98:99], v[90:91], v[132:133]
	v_pk_add_f32 v[90:91], v[88:89], v[130:131]
	v_cvt_pk_bf16_f32 v88, v92, v93
	v_cvt_pk_bf16_f32 v89, v94, v95
	v_pk_add_f32 v[86:87], v[86:87], v[136:137]
	v_cvt_pk_bf16_f32 v90, v90, v91
	v_cvt_pk_bf16_f32 v91, v98, v99
	global_store_dwordx4 v[96:97], v[88:91], off
	v_pk_add_f32 v[76:77], v[76:77], v[134:135]
	v_pk_add_f32 v[78:79], v[78:79], v[136:137]
	v_add_u32_e32 v88, 0x90, v158
	v_ashrrev_i32_e32 v89, 31, v88
	v_mul_lo_u32 v90, s30, v89
	v_mul_lo_u32 v91, s31, v88
	v_mad_u64_u32 v[88:89], s[10:11], s30, v88, 0
	v_add3_u32 v89, v89, v90, v91
	v_lshl_add_u64 v[88:89], v[88:89], 1, v[164:165]
	v_pk_add_f32 v[90:91], v[82:83], v[132:133]
	v_pk_add_f32 v[82:83], v[80:81], v[130:131]
	v_cvt_pk_bf16_f32 v80, v84, v85
	v_cvt_pk_bf16_f32 v81, v86, v87
	v_pk_add_f32 v[70:71], v[70:71], v[136:137]
	v_cvt_pk_bf16_f32 v82, v82, v83
	v_cvt_pk_bf16_f32 v83, v90, v91
	global_store_dwordx4 v[88:89], v[80:83], off
	v_pk_add_f32 v[68:69], v[68:69], v[134:135]
	s_and_b64 vcc, exec, s[8:9]
	v_add_u32_e32 v80, 0xa0, v158
	v_ashrrev_i32_e32 v81, 31, v80
	v_mul_lo_u32 v82, s30, v81
	v_mul_lo_u32 v83, s31, v80
	v_mad_u64_u32 v[80:81], s[10:11], s30, v80, 0
	v_add3_u32 v81, v81, v82, v83
	v_lshl_add_u64 v[80:81], v[80:81], 1, v[164:165]
	v_pk_add_f32 v[82:83], v[74:75], v[132:133]
	v_pk_add_f32 v[74:75], v[72:73], v[130:131]
	v_cvt_pk_bf16_f32 v72, v76, v77
	v_cvt_pk_bf16_f32 v73, v78, v79
	v_mov_b32_e32 v129, 0
	v_cvt_pk_bf16_f32 v74, v74, v75
	v_cvt_pk_bf16_f32 v75, v82, v83
	global_store_dwordx4 v[80:81], v[72:75], off
	s_nop 1
	v_add_u32_e32 v72, 0xb0, v158
	v_ashrrev_i32_e32 v73, 31, v72
	v_mul_lo_u32 v74, s30, v73
	v_mul_lo_u32 v75, s31, v72
	v_mad_u64_u32 v[72:73], s[10:11], s30, v72, 0
	v_add3_u32 v73, v73, v74, v75
	v_pk_add_f32 v[74:75], v[66:67], v[132:133]
	v_pk_add_f32 v[66:67], v[64:65], v[130:131]
	v_lshl_add_u64 v[72:73], v[72:73], 1, v[164:165]
	v_cvt_pk_bf16_f32 v64, v68, v69
	v_cvt_pk_bf16_f32 v65, v70, v71
	v_cvt_pk_bf16_f32 v66, v66, v67
	v_cvt_pk_bf16_f32 v67, v74, v75
	global_store_dwordx4 v[72:73], v[64:67], off
	v_mov_b32_e32 v130, 0
	v_mov_b32_e32 v131, 0
	v_mov_b32_e32 v64, 0
	v_mov_b32_e32 v65, 0
	v_mov_b32_e32 v66, 0
	v_mov_b32_e32 v67, 0
	s_cbranch_vccnz .LBB0_285
	global_load_dwordx4 v[128:131], v[162:163], off offset:528
	global_load_dwordx4 v[64:67], v[162:163], off offset:512
	s_waitcnt vmcnt(0)
	s_branch .LBB0_285

; __device__ __forceinline__ float shfl_idx(float v, int src) { return __int_as_float(__builtin_amdgcn_ds_bpermute(src << 2, __float_as_int(v))); }
; __device__ __forceinline__ float hw_sin_rev(float r) { return __builtin_amdgcn_sinf(r); }
; __device__ __forceinline__ void hymlp_unit(KP p, int u, int tid) {
;     ...
;   const float* w1 = p->in[12]; const float* b1 = p->in[13]; const float* w2 = p->in[14]; const float* b2 = p->in[15];
;   const float* w3 = p->in[16]; const float* b3 = p->in[17]; const float* fr = p->in[18];
;   float a = b1[lane];
;   for (int i = 0; i < 33; ++i) a += shfl_idx(z, i) * w1[i * 64 + lane];
;   float r1 = fr[lane] * a * 0.15915494309189535f; r1 -= floorf(r1);
;   float h = hw_sin_rev(r1);
;   a = b2[lane];
;   for (int i = 0; i < 64; ++i) a += shfl_idx(h, i) * w2[i * 64 + lane];
;   r1 = fr[64 + lane] * a * 0.15915494309189535f; r1 -= floorf(r1);
;   h = hw_sin_rev(r1);
;   a = b3[lane];
;   for (int i = 0; i < 64; ++i) a += shfl_idx(h, i) * w3[i * 64 + lane];
.LBB0_513:
	v_readlane_b32 s2, v253, 7
	v_readlane_b32 s3, v253, 8
	s_andn2_b64 vcc, exec, s[2:3]
	v_ashrrev_i32_e32 v22, 6, v146
	s_cbranch_vccnz .LBB0_532
	v_readlane_b32 s2, v254, 9
	v_readlane_b32 s3, v254, 10
	s_waitcnt lgkmcnt(0)
	s_load_dwordx8 s[12:19], s[2:3], 0x60
	s_load_dwordx4 s[20:23], s[2:3], 0x80
	s_nop 0
	s_load_dwordx2 s[2:3], s[2:3], 0x90
	v_and_b32_e32 v8, 63, v229
	v_cmp_ne_u32_e64 s[6:7], 0, v8
	v_cmp_gt_u32_e64 s[8:9], 33, v8
	v_cmp_lt_u32_e64 s[10:11], 16, v8
	v_lshlrev_b32_e32 v138, 2, v8
	v_lshlrev_b32_e32 v8, 1, v8
	v_mov_b32_e32 v9, v139
	v_add_u32_e32 v0, -1, v229
	s_waitcnt lgkmcnt(0)
	v_lshl_add_u64 v[2:3], s[2:3], 0, v[138:139]
	v_lshl_add_u64 v[8:9], s[0:1], 0, v[8:9]
	s_mov_b64 s[2:3], 0x26d21000
	v_and_b32_e32 v0, 15, v0
	v_lshl_add_u64 v[8:9], v[8:9], 0, s[2:3]
	v_lshl_add_u64 v[10:11], s[12:13], 0, v[138:139]
	s_mov_b64 s[2:3], 0xa00
	v_cvt_f32_ubyte0_e32 v0, v0
	v_mov_b32_e32 v1, 0x38d1b717
	v_lshl_add_u64 v[10:11], v[10:11], 0, s[2:3]
	v_lshl_add_u64 v[12:13], s[16:17], 0, v[138:139]
	s_mov_b64 s[2:3], 0x700
	v_lshl_add_u64 v[14:15], s[20:21], 0, v[138:139]
	v_fmamk_f32 v20, v0, 0x3f7fff90, v1
	v_lshl_add_u64 v[0:1], s[14:15], 0, v[138:139]
	v_lshl_add_u64 v[4:5], s[18:19], 0, v[138:139]
	v_lshl_add_u64 v[6:7], s[22:23], 0, v[138:139]
	v_lshl_add_u64 v[12:13], v[12:13], 0, s[2:3]
	v_lshl_add_u64 v[14:15], v[14:15], 0, s[2:3]
	s_mov_b32 s14, s70
	global_load_dword v225, v[0:1], off
	global_load_dword v230, v[4:5], off
	global_load_dword v231, v[6:7], off
	global_load_dword v232, v[2:3], off
	global_load_dword v233, v[2:3], off offset:256
	global_load_dword v234, v[2:3], off offset:512
	s_mov_b64 s[2:3], 0x2000
	v_lshl_add_u64 v[16:17], v[10:11], 0, s[2:3]
	global_load_dword v58, v[10:11], off offset:-2560
	global_load_dword v59, v[10:11], off offset:-2304
	global_load_dword v60, v[10:11], off offset:-2048
	global_load_dword v61, v[10:11], off offset:-1792
	global_load_dword v62, v[10:11], off offset:-1536
	global_load_dword v63, v[10:11], off offset:-1280
	global_load_dword v64, v[10:11], off offset:-1024
	global_load_dword v65, v[10:11], off offset:-768
	global_load_dword v66, v[10:11], off offset:-512
	global_load_dword v67, v[10:11], off offset:-256
	global_load_dword v68, v[10:11], off
	global_load_dword v69, v[10:11], off offset:256
	global_load_dword v70, v[10:11], off offset:512
	global_load_dword v71, v[10:11], off offset:768
	global_load_dword v72, v[10:11], off offset:1024
	global_load_dword v73, v[10:11], off offset:1280
	global_load_dword v74, v[10:11], off offset:1536
	global_load_dword v75, v[10:11], off offset:1792
	global_load_dword v76, v[10:11], off offset:2048
	global_load_dword v77, v[10:11], off offset:2304
	global_load_dword v78, v[10:11], off offset:2560
	global_load_dword v79, v[10:11], off offset:2816
	global_load_dword v80, v[10:11], off offset:3072
	global_load_dword v81, v[10:11], off offset:3328
	global_load_dword v82, v[10:11], off offset:3584
	global_load_dword v83, v[10:11], off offset:3840
	global_load_dword v84, v[16:17], off offset:-4096
	global_load_dword v85, v[16:17], off offset:-3840
	global_load_dword v86, v[16:17], off offset:-3584
	global_load_dword v87, v[16:17], off offset:-3328
	global_load_dword v88, v[16:17], off offset:-3072
	global_load_dword v89, v[16:17], off offset:-2816
	global_load_dword v90, v[16:17], off offset:-2560
	v_lshl_add_u64 v[16:17], v[12:13], 0, s[2:3]
	v_lshl_add_u64 v[18:19], v[16:17], 0, s[2:3]
	global_load_dword v91, v[12:13], off offset:-1792
	global_load_dword v92, v[12:13], off offset:-1536
	global_load_dword v93, v[12:13], off offset:-1280
	global_load_dword v94, v[12:13], off offset:-1024
	global_load_dword v95, v[12:13], off offset:-768
	global_load_dword v96, v[12:13], off offset:-512
	global_load_dword v97, v[12:13], off offset:-256
	global_load_dword v98, v[12:13], off
	global_load_dword v99, v[12:13], off offset:256
	global_load_dword v100, v[12:13], off offset:512
	global_load_dword v101, v[12:13], off offset:768
	global_load_dword v102, v[12:13], off offset:1024
	global_load_dword v103, v[12:13], off offset:1280
	global_load_dword v104, v[12:13], off offset:1536
	global_load_dword v105, v[12:13], off offset:1792
	global_load_dword v106, v[12:13], off offset:2048
	global_load_dword v107, v[12:13], off offset:2304
	global_load_dword v108, v[12:13], off offset:2560
	global_load_dword v109, v[12:13], off offset:2816
	global_load_dword v110, v[12:13], off offset:3072
	global_load_dword v111, v[12:13], off offset:3328
	global_load_dword v112, v[12:13], off offset:3584
	global_load_dword v113, v[12:13], off offset:3840
	global_load_dword v114, v[16:17], off offset:-4096
	global_load_dword v115, v[16:17], off offset:-3840
	global_load_dword v116, v[16:17], off offset:-3584
	global_load_dword v117, v[16:17], off offset:-3328
	global_load_dword v118, v[16:17], off offset:-3072
	global_load_dword v119, v[16:17], off offset:-2816
	global_load_dword v120, v[16:17], off offset:-2560
	global_load_dword v121, v[16:17], off offset:-2304
; __device__ __forceinline__ float shfl_idx(float v, int src) { return __int_as_float(__builtin_amdgcn_ds_bpermute(src << 2, __float_as_int(v))); }
; __device__ __forceinline__ float hw_sin_rev(float r) { return __builtin_amdgcn_sinf(r); }
; __device__ __forceinline__ void hymlp_unit(KP p, int u, int tid) {
;     ...
;   for (int i = 0; i < 64; ++i) a += shfl_idx(h, i) * w2[i * 64 + lane];
;   r1 = fr[64 + lane] * a * 0.15915494309189535f; r1 -= floorf(r1);
;   h = hw_sin_rev(r1);
;   a = b3[lane];
;   for (int i = 0; i < 64; ++i) a += shfl_idx(h, i) * w3[i * 64 + lane];
	global_load_dword v122, v[16:17], off offset:-2048
	global_load_dword v123, v[16:17], off offset:-1792
	global_load_dword v124, v[16:17], off offset:-1536
	global_load_dword v125, v[16:17], off offset:-1280
	global_load_dword v126, v[16:17], off offset:-1024
	global_load_dword v127, v[16:17], off offset:-768
	global_load_dword v128, v[16:17], off offset:-512
	global_load_dword v129, v[16:17], off offset:-256
	global_load_dword v130, v[16:17], off
	global_load_dword v131, v[16:17], off offset:256
	global_load_dword v132, v[16:17], off offset:512
	global_load_dword v133, v[16:17], off offset:768
	global_load_dword v134, v[16:17], off offset:1024
	global_load_dword v135, v[16:17], off offset:1280
	global_load_dword v136, v[16:17], off offset:1536
	global_load_dword v137, v[16:17], off offset:1792
	global_load_dword v140, v[16:17], off offset:2048
	global_load_dword v141, v[16:17], off offset:2304
	global_load_dword v142, v[16:17], off offset:2560
	global_load_dword v145, v[16:17], off offset:2816
	global_load_dword v148, v[16:17], off offset:3072
	global_load_dword v149, v[16:17], off offset:3328
	global_load_dword v150, v[16:17], off offset:3584
	global_load_dword v151, v[16:17], off offset:3840
	global_load_dword v152, v[18:19], off offset:-4096
	global_load_dword v153, v[18:19], off offset:-3840
	global_load_dword v154, v[18:19], off offset:-3584
	global_load_dword v155, v[18:19], off offset:-3328
	global_load_dword v156, v[18:19], off offset:-3072
	global_load_dword v157, v[18:19], off offset:-2816
	global_load_dword v158, v[18:19], off offset:-2560
	global_load_dword v159, v[18:19], off offset:-2304
	global_load_dword v160, v[18:19], off offset:-2048
	v_lshl_add_u64 v[16:17], v[14:15], 0, s[2:3]
	v_lshl_add_u64 v[18:19], v[16:17], 0, s[2:3]
	global_load_dword v161, v[14:15], off offset:-1792
	global_load_dword v162, v[14:15], off offset:-1536
	global_load_dword v163, v[14:15], off offset:-1280
	global_load_dword v164, v[14:15], off offset:-1024
	global_load_dword v165, v[14:15], off offset:-768
	global_load_dword v166, v[14:15], off offset:-512
	global_load_dword v167, v[14:15], off offset:-256
	global_load_dword v168, v[14:15], off
	global_load_dword v169, v[14:15], off offset:256
	global_load_dword v170, v[14:15], off offset:512
	global_load_dword v171, v[14:15], off offset:768
	global_load_dword v172, v[14:15], off offset:1024
	global_load_dword v173, v[14:15], off offset:1280
	global_load_dword v174, v[14:15], off offset:1536
	global_load_dword v175, v[14:15], off offset:1792
	global_load_dword v176, v[14:15], off offset:2048
	global_load_dword v177, v[14:15], off offset:2304
	global_load_dword v178, v[14:15], off offset:2560
	global_load_dword v179, v[14:15], off offset:2816
	global_load_dword v180, v[14:15], off offset:3072
	global_load_dword v181, v[14:15], off offset:3328
	global_load_dword v182, v[14:15], off offset:3584
	global_load_dword v183, v[14:15], off offset:3840
	global_load_dword v184, v[16:17], off offset:-4096
	global_load_dword v185, v[16:17], off offset:-3840
	global_load_dword v186, v[16:17], off offset:-3584
	global_load_dword v187, v[16:17], off offset:-3328
	global_load_dword v188, v[16:17], off offset:-3072
	global_load_dword v189, v[16:17], off offset:-2816
	global_load_dword v190, v[16:17], off offset:-2560
	global_load_dword v191, v[16:17], off offset:-2304
	global_load_dword v192, v[16:17], off offset:-2048
	global_load_dword v193, v[16:17], off offset:-1792
	global_load_dword v194, v[16:17], off offset:-1536
	global_load_dword v195, v[16:17], off offset:-1280
	global_load_dword v196, v[16:17], off offset:-1024
	global_load_dword v197, v[16:17], off offset:-768
	global_load_dword v198, v[16:17], off offset:-512
	global_load_dword v199, v[16:17], off offset:-256
	global_load_dword v200, v[16:17], off
	global_load_dword v201, v[16:17], off offset:256
	global_load_dword v202, v[16:17], off offset:512
	global_load_dword v203, v[16:17], off offset:768
	global_load_dword v204, v[16:17], off offset:1024
	global_load_dword v205, v[16:17], off offset:1280
	global_load_dword v206, v[16:17], off offset:1536
	global_load_dword v207, v[16:17], off offset:1792
	global_load_dword v208, v[16:17], off offset:2048
	global_load_dword v209, v[16:17], off offset:2304
	global_load_dword v210, v[16:17], off offset:2560
	global_load_dword v211, v[16:17], off offset:2816
	global_load_dword v212, v[16:17], off offset:3072
	global_load_dword v213, v[16:17], off offset:3328
	global_load_dword v214, v[16:17], off offset:3584
	global_load_dword v215, v[16:17], off offset:3840
	global_load_dword v216, v[18:19], off offset:-4096
	global_load_dword v217, v[18:19], off offset:-3840
	global_load_dword v218, v[18:19], off offset:-3584
	global_load_dword v219, v[18:19], off offset:-3328
	global_load_dword v220, v[18:19], off offset:-3072
	global_load_dword v221, v[18:19], off offset:-2816
	global_load_dword v222, v[18:19], off offset:-2560
	global_load_dword v223, v[18:19], off offset:-2304
	global_load_dword v224, v[18:19], off offset:-2048
	s_waitcnt vmcnt(0)

; __device__ __forceinline__ float shfl_idx(float v, int src) { return __int_as_float(__builtin_amdgcn_ds_bpermute(src << 2, __float_as_int(v))); }
; __device__ __forceinline__ float hw_sin_rev(float r) { return __builtin_amdgcn_sinf(r); }
; __device__ __forceinline__ void hymlp_unit(KP p, int u, int tid) {
;     ...
;   for (int i = 0; i < 33; ++i) a += shfl_idx(z, i) * w1[i * 64 + lane];
;   float r1 = fr[lane] * a * 0.15915494309189535f; r1 -= floorf(r1);
;   float h = hw_sin_rev(r1);
;   a = b2[lane];
;   for (int i = 0; i < 64; ++i) a += shfl_idx(h, i) * w2[i * 64 + lane];
;   r1 = fr[64 + lane] * a * 0.15915494309189535f; r1 -= floorf(r1);
;   h = hw_sin_rev(r1);
.LBB0_525:
	s_or_b64 exec, exec, s[2:3]
	s_nop 1
	v_mov_b32_e32 v21, v225
	v_readlane_b32 s2, v17, 0
	v_readlane_b32 s3, v17, 1
	v_readlane_b32 s4, v17, 2
	v_readlane_b32 s5, v17, 3
	v_readlane_b32 s12, v17, 4
	v_readlane_b32 s13, v17, 5
	v_readlane_b32 s15, v17, 6
	v_readlane_b32 s16, v17, 7
	v_fmac_f32_e32 v21, s2, v58
	v_fmac_f32_e32 v21, s3, v59
	v_fmac_f32_e32 v21, s4, v60
	v_fmac_f32_e32 v21, s5, v61
	v_fmac_f32_e32 v21, s12, v62
	v_fmac_f32_e32 v21, s13, v63
	v_fmac_f32_e32 v21, s15, v64
	v_fmac_f32_e32 v21, s16, v65
	v_readlane_b32 s2, v17, 8
	v_readlane_b32 s3, v17, 9
	v_readlane_b32 s4, v17, 10
	v_readlane_b32 s5, v17, 11
	v_readlane_b32 s12, v17, 12
	v_readlane_b32 s13, v17, 13
	v_readlane_b32 s15, v17, 14
	v_readlane_b32 s16, v17, 15
	v_fmac_f32_e32 v21, s2, v66
	v_fmac_f32_e32 v21, s3, v67
	v_fmac_f32_e32 v21, s4, v68
	v_fmac_f32_e32 v21, s5, v69
	v_fmac_f32_e32 v21, s12, v70
	v_fmac_f32_e32 v21, s13, v71
	v_fmac_f32_e32 v21, s15, v72
	v_fmac_f32_e32 v21, s16, v73
	v_readlane_b32 s2, v17, 16
	v_readlane_b32 s3, v17, 17
	v_readlane_b32 s4, v17, 18
	v_readlane_b32 s5, v17, 19
	v_readlane_b32 s12, v17, 20
	v_readlane_b32 s13, v17, 21
	v_readlane_b32 s15, v17, 22
	v_readlane_b32 s16, v17, 23
	v_fmac_f32_e32 v21, s2, v74
	v_fmac_f32_e32 v21, s3, v75
	v_fmac_f32_e32 v21, s4, v76
	v_fmac_f32_e32 v21, s5, v77
	v_fmac_f32_e32 v21, s12, v78
	v_fmac_f32_e32 v21, s13, v79
	v_fmac_f32_e32 v21, s15, v80
	v_fmac_f32_e32 v21, s16, v81
	v_readlane_b32 s2, v17, 24
	v_readlane_b32 s3, v17, 25
	v_readlane_b32 s4, v17, 26
	v_readlane_b32 s5, v17, 27
	v_readlane_b32 s12, v17, 28
	v_readlane_b32 s13, v17, 29
	v_readlane_b32 s15, v17, 30
	v_readlane_b32 s16, v17, 31
	v_fmac_f32_e32 v21, s2, v82
	v_fmac_f32_e32 v21, s3, v83
	v_fmac_f32_e32 v21, s4, v84
	v_fmac_f32_e32 v21, s5, v85
	v_fmac_f32_e32 v21, s12, v86
	v_fmac_f32_e32 v21, s13, v87
	v_fmac_f32_e32 v21, s15, v88
	v_fmac_f32_e32 v21, s16, v89
	v_readlane_b32 s2, v17, 32
	s_nop 1
	v_fmac_f32_e32 v21, s2, v90
	v_mul_f32_e32 v18, v21, v232
	v_mul_f32_e32 v19, 0.15915494, v18
	v_floor_f32_e32 v19, v19
	v_fma_f32 v18, v18, 0.15915494, -v19
	v_sin_f32_e32 v21, v18
	s_nop 1
	v_mov_b32_e32 v17, v230
	v_readlane_b32 s2, v21, 0
	v_readlane_b32 s3, v21, 1
	v_readlane_b32 s4, v21, 2
	v_readlane_b32 s5, v21, 3
	v_readlane_b32 s12, v21, 4
	v_readlane_b32 s13, v21, 5
	v_readlane_b32 s15, v21, 6
	v_readlane_b32 s16, v21, 7
	v_fmac_f32_e32 v17, s2, v91
	v_fmac_f32_e32 v17, s3, v92
	v_fmac_f32_e32 v17, s4, v93
	v_fmac_f32_e32 v17, s5, v94
	v_fmac_f32_e32 v17, s12, v95
	v_fmac_f32_e32 v17, s13, v96
	v_fmac_f32_e32 v17, s15, v97
	v_fmac_f32_e32 v17, s16, v98
	v_readlane_b32 s2, v21, 8
	v_readlane_b32 s3, v21, 9
	v_readlane_b32 s4, v21, 10
	v_readlane_b32 s5, v21, 11
	v_readlane_b32 s12, v21, 12
	v_readlane_b32 s13, v21, 13
	v_readlane_b32 s15, v21, 14
	v_readlane_b32 s16, v21, 15
	v_fmac_f32_e32 v17, s2, v99
	v_fmac_f32_e32 v17, s3, v100
	v_fmac_f32_e32 v17, s4, v101
	v_fmac_f32_e32 v17, s5, v102
	v_fmac_f32_e32 v17, s12, v103
	v_fmac_f32_e32 v17, s13, v104
	v_fmac_f32_e32 v17, s15, v105
	v_fmac_f32_e32 v17, s16, v106
	v_readlane_b32 s2, v21, 16
	v_readlane_b32 s3, v21, 17
	v_readlane_b32 s4, v21, 18
	v_readlane_b32 s5, v21, 19
	v_readlane_b32 s12, v21, 20
	v_readlane_b32 s13, v21, 21
	v_readlane_b32 s15, v21, 22
	v_readlane_b32 s16, v21, 23
	v_fmac_f32_e32 v17, s2, v107
	v_fmac_f32_e32 v17, s3, v108
	v_fmac_f32_e32 v17, s4, v109
	v_fmac_f32_e32 v17, s5, v110
	v_fmac_f32_e32 v17, s12, v111
	v_fmac_f32_e32 v17, s13, v112
	v_fmac_f32_e32 v17, s15, v113
	v_fmac_f32_e32 v17, s16, v114
	v_readlane_b32 s2, v21, 24
	v_readlane_b32 s3, v21, 25
	v_readlane_b32 s4, v21, 26
	v_readlane_b32 s5, v21, 27
	v_readlane_b32 s12, v21, 28
	v_readlane_b32 s13, v21, 29
	v_readlane_b32 s15, v21, 30
	v_readlane_b32 s16, v21, 31
	v_fmac_f32_e32 v17, s2, v115
	v_fmac_f32_e32 v17, s3, v116
	v_fmac_f32_e32 v17, s4, v117
	v_fmac_f32_e32 v17, s5, v118
	v_fmac_f32_e32 v17, s12, v119
	v_fmac_f32_e32 v17, s13, v120
	v_fmac_f32_e32 v17, s15, v121
	v_fmac_f32_e32 v17, s16, v122
	v_readlane_b32 s2, v21, 32
	v_readlane_b32 s3, v21, 33
	v_readlane_b32 s4, v21, 34
	v_readlane_b32 s5, v21, 35
	v_readlane_b32 s12, v21, 36
	v_readlane_b32 s13, v21, 37
	v_readlane_b32 s15, v21, 38
	v_readlane_b32 s16, v21, 39
	v_fmac_f32_e32 v17, s2, v123
	v_fmac_f32_e32 v17, s3, v124
	v_fmac_f32_e32 v17, s4, v125
	v_fmac_f32_e32 v17, s5, v126
	v_fmac_f32_e32 v17, s12, v127
	v_fmac_f32_e32 v17, s13, v128
	v_fmac_f32_e32 v17, s15, v129
	v_fmac_f32_e32 v17, s16, v130
	v_readlane_b32 s2, v21, 40
	v_readlane_b32 s3, v21, 41
	v_readlane_b32 s4, v21, 42
	v_readlane_b32 s5, v21, 43
	v_readlane_b32 s12, v21, 44
	v_readlane_b32 s13, v21, 45
	v_readlane_b32 s15, v21, 46
	v_readlane_b32 s16, v21, 47
	v_fmac_f32_e32 v17, s2, v131
	v_fmac_f32_e32 v17, s3, v132
	v_fmac_f32_e32 v17, s4, v133
	v_fmac_f32_e32 v17, s5, v134
	v_fmac_f32_e32 v17, s12, v135
	v_fmac_f32_e32 v17, s13, v136
	v_fmac_f32_e32 v17, s15, v137
	v_fmac_f32_e32 v17, s16, v140
	v_readlane_b32 s2, v21, 48
	v_readlane_b32 s3, v21, 49
	v_readlane_b32 s4, v21, 50
	v_readlane_b32 s5, v21, 51
	v_readlane_b32 s12, v21, 52
	v_readlane_b32 s13, v21, 53
	v_readlane_b32 s15, v21, 54
	v_readlane_b32 s16, v21, 55
	v_fmac_f32_e32 v17, s2, v141
	v_fmac_f32_e32 v17, s3, v142
; __device__ __forceinline__ bf16_t f2bf(float f) { return (bf16_t)(cvt_pk_bf16(f, 0.f) & 0xffffu); }
; __device__ __forceinline__ float bf2f(bf16_t b) { return __uint_as_float(((unsigned)b) << 16); }
; __device__ __forceinline__ float shfl_idx(float v, int src) { return __int_as_float(__builtin_amdgcn_ds_bpermute(src << 2, __float_as_int(v))); }
; __device__ __forceinline__ float hw_sin_rev(float r) { return __builtin_amdgcn_sinf(r); }
; __device__ __forceinline__ void hymlp_unit(KP p, int u, int tid) {
;     ...
;   for (int i = 0; i < 64; ++i) a += shfl_idx(h, i) * w2[i * 64 + lane];
;   r1 = fr[64 + lane] * a * 0.15915494309189535f; r1 -= floorf(r1);
;   h = hw_sin_rev(r1);
;   a = b3[lane];
;   for (int i = 0; i < 64; ++i) a += shfl_idx(h, i) * w3[i * 64 + lane];
;   r1 = fr[128 + lane] * a * 0.15915494309189535f; r1 -= floorf(r1);
;   h = hw_sin_rev(r1);
;   bf16_t* H3 = (bf16_t*)(p->ws + WS_H3PAD) + (size_t)t * 256;
;   const bf16_t hi = f2bf(h); const bf16_t lo = f2bf(h - bf2f(hi));
;   H3[lane] = hi; H3[64 + lane] = hi; H3[128 + lane] = lo; H3[192 + lane] = 0;
	v_fmac_f32_e32 v17, s4, v145
	v_fmac_f32_e32 v17, s5, v148
	v_fmac_f32_e32 v17, s12, v149
	v_fmac_f32_e32 v17, s13, v150
	v_fmac_f32_e32 v17, s15, v151
	v_fmac_f32_e32 v17, s16, v152
	v_readlane_b32 s2, v21, 56
	v_readlane_b32 s3, v21, 57
	v_readlane_b32 s4, v21, 58
	v_readlane_b32 s5, v21, 59
	v_readlane_b32 s12, v21, 60
	v_readlane_b32 s13, v21, 61
	v_readlane_b32 s15, v21, 62
	v_readlane_b32 s16, v21, 63
	v_fmac_f32_e32 v17, s2, v153
	v_fmac_f32_e32 v17, s3, v154
	v_fmac_f32_e32 v17, s4, v155
	v_fmac_f32_e32 v17, s5, v156
	v_fmac_f32_e32 v17, s12, v157
	v_fmac_f32_e32 v17, s13, v158
	v_fmac_f32_e32 v17, s15, v159
	v_fmac_f32_e32 v17, s16, v160
	v_mul_f32_e32 v18, v17, v233
	v_mul_f32_e32 v19, 0.15915494, v18
	v_floor_f32_e32 v19, v19
	v_fma_f32 v18, v18, 0.15915494, -v19
	v_sin_f32_e32 v17, v18
	s_nop 1
	v_mov_b32_e32 v21, v231
	v_readlane_b32 s2, v17, 0
	v_readlane_b32 s3, v17, 1
	v_readlane_b32 s4, v17, 2
	v_readlane_b32 s5, v17, 3
	v_readlane_b32 s12, v17, 4
	v_readlane_b32 s13, v17, 5
	v_readlane_b32 s15, v17, 6
	v_readlane_b32 s16, v17, 7
	v_fmac_f32_e32 v21, s2, v161
	v_fmac_f32_e32 v21, s3, v162
	v_fmac_f32_e32 v21, s4, v163
	v_fmac_f32_e32 v21, s5, v164
	v_fmac_f32_e32 v21, s12, v165
	v_fmac_f32_e32 v21, s13, v166
	v_fmac_f32_e32 v21, s15, v167
	v_fmac_f32_e32 v21, s16, v168
	v_readlane_b32 s2, v17, 8
	v_readlane_b32 s3, v17, 9
	v_readlane_b32 s4, v17, 10
	v_readlane_b32 s5, v17, 11
	v_readlane_b32 s12, v17, 12
	v_readlane_b32 s13, v17, 13
	v_readlane_b32 s15, v17, 14
	v_readlane_b32 s16, v17, 15
	v_fmac_f32_e32 v21, s2, v169
	v_fmac_f32_e32 v21, s3, v170
	v_fmac_f32_e32 v21, s4, v171
	v_fmac_f32_e32 v21, s5, v172
	v_fmac_f32_e32 v21, s12, v173
	v_fmac_f32_e32 v21, s13, v174
	v_fmac_f32_e32 v21, s15, v175
	v_fmac_f32_e32 v21, s16, v176
	v_readlane_b32 s2, v17, 16
	v_readlane_b32 s3, v17, 17
	v_readlane_b32 s4, v17, 18
	v_readlane_b32 s5, v17, 19
	v_readlane_b32 s12, v17, 20
	v_readlane_b32 s13, v17, 21
	v_readlane_b32 s15, v17, 22
	v_readlane_b32 s16, v17, 23
	v_fmac_f32_e32 v21, s2, v177
	v_fmac_f32_e32 v21, s3, v178
	v_fmac_f32_e32 v21, s4, v179
	v_fmac_f32_e32 v21, s5, v180
	v_fmac_f32_e32 v21, s12, v181
	v_fmac_f32_e32 v21, s13, v182
	v_fmac_f32_e32 v21, s15, v183
	v_fmac_f32_e32 v21, s16, v184
	v_readlane_b32 s2, v17, 24
	v_readlane_b32 s3, v17, 25
	v_readlane_b32 s4, v17, 26
	v_readlane_b32 s5, v17, 27
	v_readlane_b32 s12, v17, 28
	v_readlane_b32 s13, v17, 29
	v_readlane_b32 s15, v17, 30
	v_readlane_b32 s16, v17, 31
	v_fmac_f32_e32 v21, s2, v185
	v_fmac_f32_e32 v21, s3, v186
	v_fmac_f32_e32 v21, s4, v187
	v_fmac_f32_e32 v21, s5, v188
	v_fmac_f32_e32 v21, s12, v189
	v_fmac_f32_e32 v21, s13, v190
	v_fmac_f32_e32 v21, s15, v191
	v_fmac_f32_e32 v21, s16, v192
	v_readlane_b32 s2, v17, 32
	v_readlane_b32 s3, v17, 33
	v_readlane_b32 s4, v17, 34
	v_readlane_b32 s5, v17, 35
	v_readlane_b32 s12, v17, 36
	v_readlane_b32 s13, v17, 37
	v_readlane_b32 s15, v17, 38
	v_readlane_b32 s16, v17, 39
	v_fmac_f32_e32 v21, s2, v193
	v_fmac_f32_e32 v21, s3, v194
	v_fmac_f32_e32 v21, s4, v195
	v_fmac_f32_e32 v21, s5, v196
	v_fmac_f32_e32 v21, s12, v197
	v_fmac_f32_e32 v21, s13, v198
	v_fmac_f32_e32 v21, s15, v199
	v_fmac_f32_e32 v21, s16, v200
	v_readlane_b32 s2, v17, 40
	v_readlane_b32 s3, v17, 41
	v_readlane_b32 s4, v17, 42
	v_readlane_b32 s5, v17, 43
	v_readlane_b32 s12, v17, 44
	v_readlane_b32 s13, v17, 45
	v_readlane_b32 s15, v17, 46
	v_readlane_b32 s16, v17, 47
	v_fmac_f32_e32 v21, s2, v201
	v_fmac_f32_e32 v21, s3, v202
	v_fmac_f32_e32 v21, s4, v203
	v_fmac_f32_e32 v21, s5, v204
	v_fmac_f32_e32 v21, s12, v205
	v_fmac_f32_e32 v21, s13, v206
	v_fmac_f32_e32 v21, s15, v207
	v_fmac_f32_e32 v21, s16, v208
	v_readlane_b32 s2, v17, 48
	v_readlane_b32 s3, v17, 49
	v_readlane_b32 s4, v17, 50
	v_readlane_b32 s5, v17, 51
	v_readlane_b32 s12, v17, 52
	v_readlane_b32 s13, v17, 53
	v_readlane_b32 s15, v17, 54
	v_readlane_b32 s16, v17, 55
	v_fmac_f32_e32 v21, s2, v209
	v_fmac_f32_e32 v21, s3, v210
	v_fmac_f32_e32 v21, s4, v211
	v_fmac_f32_e32 v21, s5, v212
	v_fmac_f32_e32 v21, s12, v213
	v_fmac_f32_e32 v21, s13, v214
	v_fmac_f32_e32 v21, s15, v215
	v_fmac_f32_e32 v21, s16, v216
	v_readlane_b32 s2, v17, 56
	v_readlane_b32 s3, v17, 57
	v_readlane_b32 s4, v17, 58
	v_readlane_b32 s5, v17, 59
	v_readlane_b32 s12, v17, 60
	v_readlane_b32 s13, v17, 61
	v_readlane_b32 s15, v17, 62
	v_readlane_b32 s16, v17, 63
	v_fmac_f32_e32 v21, s2, v217
	v_fmac_f32_e32 v21, s3, v218
	v_fmac_f32_e32 v21, s4, v219
	v_fmac_f32_e32 v21, s5, v220
	v_fmac_f32_e32 v21, s12, v221
	v_fmac_f32_e32 v21, s13, v222
	v_fmac_f32_e32 v21, s15, v223
	v_fmac_f32_e32 v21, s16, v224
	v_ashrrev_i32_e32 v17, 31, v16
	s_add_i32 s14, s14, s86
	v_lshlrev_b64 v[16:17], 9, v[16:17]
	s_cmpk_gt_i32 s14, 0x7ff
	v_lshl_add_u64 v[16:17], v[8:9], 0, v[16:17]
	v_mul_f32_e32 v18, v21, v234
	v_mul_f32_e32 v19, 0.15915494, v18
	v_floor_f32_e32 v19, v19
	v_fma_f32 v18, v18, 0.15915494, -v19
	v_sin_f32_e32 v18, v18
	s_nop 0
	v_cvt_pk_bf16_f32 v19, v18, v139
	s_nop 0
	v_lshlrev_b32_e32 v21, 16, v19
	v_sub_f32_e32 v18, v18, v21
	s_nop 0
	v_cvt_pk_bf16_f32 v18, v18, v139
	global_store_short v[16:17], v19, off
	global_store_short v[16:17], v19, off offset:128
	global_store_short v[16:17], v18, off offset:256
	global_store_short v[16:17], v139, off offset:384
	s_cbranch_scc0 .Lhy_unit
